# v018 + tile-order decode at the tile-loop edge: group height is provably 8, runtime integer division (rcp chain + readfirstlane) replaced by shift/mask in all three GEMM tile loops
# speedup vs baseline: 1.0099x; 1.0006x over previous
;     __device__ bool next(int i, Unit& u) const {
;     ...
;         int wgid = (int)L; { const int q = nwg / NXCD, r = nwg % NXCD, xcd = wgid % NXCD, off = wgid / NXCD; wgid = (xcd < r ? xcd * (q + 1) : r * (q + 1) + (xcd - r) * q) + off; }
;         const int nig = WGM * nN, gid = wgid / nig, fm = gid * WGM, gsz = (nM - fm) < WGM ? (nM - fm) : WGM;
;         u.pm = fm + ((wgid % nig) % gsz); u.pn = (wgid % nig) / gsz; return true;
.LBB0_97:
	s_andn2_b64 vcc, exec, s[26:27]
	s_cbranch_vccnz .LBB0_99
	s_ashr_i32 s3, s34, 31
	s_lshr_b32 s3, s3, 29
	s_add_i32 s3, s34, s3
	s_ashr_i32 s7, s3, 3
	s_and_b32 s3, s3, -8
	s_sub_i32 s3, s34, s3
	s_lshr_b32 s26, s3, 31
	s_or_b32 s26, s69, s26
	s_mul_i32 s3, s3, s26
	s_add_i32 s3, s3, s7
	s_abs_i32 s26, s3
	v_readlane_b32 s27, v255, 59
	s_mul_hi_u32 s27, s26, s27
	s_mul_i32 s34, s27, s85
	s_ashr_i32 s7, s3, 31
	s_sub_i32 s26, s26, s34
	s_xor_b32 s7, s7, s95
	s_add_i32 s34, s27, 1
	s_sub_i32 s35, s26, s85
	s_cmp_ge_u32 s26, s85
	s_cselect_b32 s27, s34, s27
	s_cselect_b32 s26, s35, s26
	s_add_i32 s34, s27, 1
	s_cmp_ge_u32 s26, s85
	s_cselect_b32 s26, s34, s27
	s_xor_b32 s26, s26, s7
	s_sub_i32 s7, s26, s7
	s_lshl_b32 s26, s7, 3
	s_mul_i32 s7, s7, s73
	s_sub_i32 s3, s3, s7
	s_lshr_b32 s82, s3, 3
	s_and_b32 s3, s3, 7
	s_add_i32 s3, s3, s26

;     __device__ bool next(int i, Unit& u) const {
;     ...
;         int wgid = (int)L; { const int q = nwg / NXCD, r = nwg % NXCD, xcd = wgid % NXCD, off = wgid / NXCD; wgid = (xcd < r ? xcd * (q + 1) : r * (q + 1) + (xcd - r) * q) + off; }
;         const int nig = WGM * nN, gid = wgid / nig, fm = gid * WGM, gsz = (nM - fm) < WGM ? (nM - fm) : WGM;
;         u.pm = fm + ((wgid % nig) % gsz); u.pn = (wgid % nig) / gsz; return true;
.LBB0_198:
	s_ashr_i32 s8, s38, 3
	s_add_i32 s8, s56, s8
	s_ashr_i32 s9, s8, 31
	s_lshr_b32 s9, s9, 27
	s_add_i32 s9, s8, s9
	s_ashr_i32 s38, s9, 5
	s_lshl_b32 s38, s38, 3
	s_andn2_b32 s9, s9, 31
	s_sub_i32 s8, s8, s9
	s_lshr_b32 s92, s8, 3
	s_and_b32 s8, s8, 7
	s_add_i32 s93, s38, s8

;     __device__ bool next(int i, Unit& u) const {
;         const long L = (long)i * G + c; if (L >= total) return false;
;         if (L >= nwg) { const int e = (int)L - nwg; u.pm = nM + e % exM; u.pn = nN + e / exM; return true; }
;         int wgid = (int)L; { const int q = nwg / NXCD, r = nwg % NXCD, xcd = wgid % NXCD, off = wgid / NXCD; wgid = (xcd < r ? xcd * (q + 1) : r * (q + 1) + (xcd - r) * q) + off; }
;         const int nig = WGM * nN, gid = wgid / nig, fm = gid * WGM, gsz = (nM - fm) < WGM ? (nM - fm) : WGM;
;         u.pm = fm + ((wgid % nig) % gsz); u.pn = (wgid % nig) / gsz; return true;
.LBB0_316:
	s_add_i32 s47, s47, 1
	s_mul_i32 s4, s47, s43
	s_mul_hi_u32 s5, s47, s44
	s_add_i32 s5, s5, s4
	s_mul_i32 s4, s47, s44
	s_add_u32 s16, s4, s45
	s_addc_u32 s17, s5, s36
	v_cmp_gt_i64_e32 vcc, s[16:17], v[188:189]
	v_cmp_lt_i64_e64 s[4:5], s[16:17], v[186:187]
	s_mov_b32 s48, s6
	s_cbranch_vccnz .LBB0_318
	s_ashr_i32 s10, s16, 31
	s_lshr_b32 s10, s10, 29
	s_add_i32 s10, s16, s10
	s_ashr_i32 s11, s10, 3
	s_and_b32 s10, s10, -8
	s_sub_i32 s10, s16, s10
	s_cmp_lt_i32 s10, 0
	s_cselect_b32 s12, s66, 0x160
	s_mul_i32 s10, s10, s12
	s_add_i32 s10, s10, s11
	s_mul_hi_i32 s11, s10, 0x2e8ba2e9
	s_lshr_b32 s12, s11, 31
	s_ashr_i32 s11, s11, 5
	s_add_i32 s11, s11, s12
	s_lshl_b32 s12, s11, 3
	s_mulk_i32 s11, 0xb0
	s_sub_i32 s11, s10, s11
	s_lshr_b32 s10, s11, 3
	s_and_b32 s11, s11, 7
	s_add_i32 s48, s12, s11
	s_mov_b32 s12, s48
